# LN1 main loop also stops at the last real row (the padding tail rows of workgroups 160..255 are never output); those workgroups carry the sixth FFN2 block
# baseline (speedup 1.0000x reference)
.LBB0_476:
	s_cmpk_gt_i32 s10, 0x213f
	s_cselect_b64 s[0:1], -1, 0
	s_and_b64 s[12:13], s[0:1], exec
	s_cselect_b32 s12, 14, 16
	s_or_b64 s[0:1], s[4:5], s[0:1]
	s_and_b64 vcc, exec, s[0:1]
	s_cbranch_vccnz .LBB0_481
	s_ashr_i32 s11, s10, 31
	s_lshl_b64 s[12:13], s[10:11], 13
	v_readlane_b32 s0, v254, 41
	v_lshlrev_b32_e32 v128, 3, v223
	v_readlane_b32 s1, v254, 42
	s_add_u32 s0, s0, s12
	v_ashrrev_i32_e32 v129, 31, v128
	s_addc_u32 s1, s1, s13
	v_lshlrev_b64 v[162:163], 1, v[128:129]
	v_lshl_add_u64 v[142:143], s[0:1], 0, v[162:163]
	global_load_dwordx4 v[130:133], v[142:143], off offset:1024 nt
	global_load_dwordx4 v[134:137], v[142:143], off offset:2048 nt
	global_load_dwordx4 v[194:197], v[142:143], off offset:3072 nt
	global_load_dwordx4 v[138:141], v[142:143], off nt
	v_add_co_u32_e32 v146, vcc, s14, v142
	s_mov_b32 s0, 0xf800000
	s_nop 0
	v_addc_co_u32_e32 v147, vcc, 0, v143, vcc
	global_load_dwordx4 v[142:145], v[146:147], off nt
	global_load_dwordx4 v[204:207], v[146:147], off offset:1024 nt
	global_load_dwordx4 v[216:219], v[146:147], off offset:2048 nt
	global_load_dwordx4 v[228:231], v[146:147], off offset:3072 nt
	s_waitcnt vmcnt(7)
	v_lshlrev_b32_e32 v188, 16, v130
	v_and_b32_e32 v189, 0xffff0000, v130
	v_lshlrev_b32_e32 v190, 16, v131
	s_waitcnt vmcnt(4)
	v_lshlrev_b32_e32 v199, 16, v139
	v_lshlrev_b32_e32 v198, 16, v138
	v_and_b32_e32 v209, 0xffff0000, v139
	v_and_b32_e32 v208, 0xffff0000, v138
	v_lshlrev_b32_e32 v201, 16, v141
	v_lshlrev_b32_e32 v200, 16, v140
	v_and_b32_e32 v215, 0xffff0000, v141
	v_and_b32_e32 v214, 0xffff0000, v140
	s_waitcnt vmcnt(2)
	v_lshlrev_b32_e32 v158, 16, v206
	v_and_b32_e32 v159, 0xffff0000, v206
	v_lshlrev_b32_e32 v160, 16, v207
	v_and_b32_e32 v161, 0xffff0000, v207
	v_pk_add_f32 v[202:203], v[198:199], v[208:209]
	v_pk_add_f32 v[206:207], v[200:201], v[214:215]
	v_and_b32_e32 v191, 0xffff0000, v131
	v_add_f32_e32 v131, v202, v203
	v_pk_add_f32 v[202:203], v[206:207], v[206:207] op_sel_hi:[0,1]
	v_lshlrev_b32_e32 v182, 16, v132
	v_and_b32_e32 v186, 0xffff0000, v132
	v_lshlrev_b32_e32 v180, 16, v133
	v_and_b32_e32 v184, 0xffff0000, v133
	v_add_f32_e32 v183, v188, v189
	v_add_f32_e32 v187, v190, v191
	v_add_f32_e32 v185, 0, v131
	v_mov_b32_e32 v181, v203
	v_lshlrev_b32_e32 v152, 16, v194
	v_and_b32_e32 v156, 0xffff0000, v194
	v_lshlrev_b32_e32 v150, 16, v195
	v_and_b32_e32 v154, 0xffff0000, v195
	v_lshlrev_b32_e32 v195, 16, v135
	v_lshlrev_b32_e32 v194, 16, v134
	v_and_b32_e32 v211, 0xffff0000, v135
	v_and_b32_e32 v210, 0xffff0000, v134
	v_pk_add_f32 v[206:207], v[182:183], v[186:187]
	v_pk_add_f32 v[202:203], v[180:181], v[184:185]
	v_pk_add_f32 v[212:213], v[194:195], v[210:211]
	v_pk_add_f32 v[202:203], v[206:207], v[202:203]
	v_lshlrev_b32_e32 v164, 16, v136
	v_and_b32_e32 v165, 0xffff0000, v136
	v_lshlrev_b32_e32 v166, 16, v137
	v_and_b32_e32 v167, 0xffff0000, v137
	v_pk_add_f32 v[212:213], v[212:213], v[212:213] op_sel_hi:[0,1]
	v_pk_add_f32 v[202:203], v[202:203], v[202:203] op_sel_hi:[0,1]
	v_add_f32_e32 v153, v164, v165
	v_add_f32_e32 v157, v166, v167
	v_mov_b32_e32 v151, v213
	v_mov_b32_e32 v155, v203
	v_lshlrev_b32_e32 v176, 16, v142
	v_and_b32_e32 v177, 0xffff0000, v142
	v_lshlrev_b32_e32 v170, 16, v144
	v_and_b32_e32 v174, 0xffff0000, v144
	s_waitcnt vmcnt(1)
	v_lshlrev_b32_e32 v144, 16, v216
	v_and_b32_e32 v148, 0xffff0000, v216
	v_lshlrev_b32_e32 v142, 16, v217
	v_and_b32_e32 v146, 0xffff0000, v217
	v_pk_add_f32 v[216:217], v[152:153], v[156:157]
	v_pk_add_f32 v[202:203], v[150:151], v[154:155]
	v_lshlrev_b32_e32 v193, 16, v197
	v_pk_add_f32 v[202:203], v[216:217], v[202:203]
	v_lshlrev_b32_e32 v192, 16, v196
	v_and_b32_e32 v217, 0xffff0000, v197
	v_and_b32_e32 v216, 0xffff0000, v196
	v_pk_add_f32 v[196:197], v[192:193], v[216:217]
	v_lshlrev_b32_e32 v178, 16, v143
	v_and_b32_e32 v179, 0xffff0000, v143
	v_pk_add_f32 v[202:203], v[202:203], v[202:203] op_sel_hi:[0,1]
	v_pk_add_f32 v[196:197], v[196:197], v[196:197] op_sel_hi:[0,1]
	v_lshlrev_b32_e32 v168, 16, v145
	v_and_b32_e32 v172, 0xffff0000, v145
	v_add_f32_e32 v171, v176, v177
	v_add_f32_e32 v175, v178, v179
	v_mov_b32_e32 v169, v197
	v_mov_b32_e32 v173, v203
	v_pk_add_f32 v[206:207], v[170:171], v[174:175]
	v_pk_add_f32 v[196:197], v[168:169], v[172:173]
	v_lshlrev_b32_e32 v203, 16, v205
	v_lshlrev_b32_e32 v202, 16, v204
	v_and_b32_e32 v213, 0xffff0000, v205
	v_and_b32_e32 v212, 0xffff0000, v204
	v_pk_add_f32 v[196:197], v[206:207], v[196:197]
	v_pk_add_f32 v[204:205], v[202:203], v[212:213]
	v_pk_add_f32 v[196:197], v[196:197], v[196:197] op_sel_hi:[0,1]
	v_pk_add_f32 v[204:205], v[204:205], v[204:205] op_sel_hi:[0,1]
	v_add_f32_e32 v145, v158, v159
	v_add_f32_e32 v149, v160, v161
	v_mov_b32_e32 v143, v205
	v_mov_b32_e32 v147, v197
	v_pk_add_f32 v[206:207], v[144:145], v[148:149]
	v_pk_add_f32 v[196:197], v[142:143], v[146:147]
	s_waitcnt vmcnt(0)
	v_lshlrev_b32_e32 v138, 16, v228
	v_pk_add_f32 v[196:197], v[206:207], v[196:197]
	v_and_b32_e32 v207, 0xffff0000, v219
	v_pk_add_f32 v[204:205], v[196:197], v[196:197] op_sel_hi:[0,1]
	v_lshlrev_b32_e32 v197, 16, v219
	v_lshlrev_b32_e32 v196, 16, v218
	v_and_b32_e32 v206, 0xffff0000, v218
	v_pk_add_f32 v[218:219], v[196:197], v[206:207]
	v_and_b32_e32 v139, 0xffff0000, v228
	v_lshlrev_b32_e32 v140, 16, v229
	v_and_b32_e32 v141, 0xffff0000, v229
	v_pk_add_f32 v[218:219], v[218:219], v[218:219] op_sel_hi:[0,1]
	v_lshlrev_b32_e32 v132, 16, v230
	v_and_b32_e32 v136, 0xffff0000, v230
	v_lshlrev_b32_e32 v130, 16, v231
	v_and_b32_e32 v134, 0xffff0000, v231
	v_add_f32_e32 v133, v138, v139
	v_add_f32_e32 v137, v140, v141
	v_mov_b32_e32 v131, v219
	v_mov_b32_e32 v135, v205
	v_pk_add_f32 v[220:221], v[132:133], v[136:137]
	v_pk_add_f32 v[204:205], v[130:131], v[134:135]
	v_and_b32_e32 v135, 64, v227
	v_pk_add_f32 v[204:205], v[220:221], v[204:205]
	v_xor_b32_e32 v133, 16, v227
	v_add_f32_e32 v131, v204, v205
	v_add_u32_e32 v135, 64, v135
	v_cmp_lt_i32_e32 vcc, v133, v135
	v_add_f32_dpp v131, v131, v131 quad_perm:[1,0,3,2] row_mask:0xf bank_mask:0xf bound_ctrl:1
	s_nop 0
	v_cndmask_b32_e32 v133, v227, v133, vcc
	v_add_f32_dpp v131, v131, v131 quad_perm:[2,3,0,1] row_mask:0xf bank_mask:0xf bound_ctrl:1
	v_lshlrev_b32_e32 v137, 2, v133
	s_nop 0
	v_add_f32_dpp v131, v131, v131 row_half_mirror row_mask:0xf bank_mask:0xf bound_ctrl:1
	s_nop 1
	v_add_f32_dpp v131, v131, v131 row_mirror row_mask:0xf bank_mask:0xf bound_ctrl:1
	ds_bpermute_b32 v133, v137, v131
	s_waitcnt lgkmcnt(0)
	v_add_f32_e32 v131, v131, v133
	v_xor_b32_e32 v133, 32, v227
	v_cmp_lt_i32_e32 vcc, v133, v135
	s_nop 1
	v_cndmask_b32_e32 v133, v227, v133, vcc
	v_lshlrev_b32_e32 v135, 2, v133
	ds_bpermute_b32 v133, v135, v131
	s_waitcnt lgkmcnt(0)
	v_add_f32_e32 v131, v131, v133
	v_fmac_f32_e32 v208, 0xb9800000, v131
	v_fmac_f32_e32 v209, 0xb9800000, v131
	v_fmac_f32_e32 v199, 0xb9800000, v131
	v_fmac_f32_e32 v198, 0xb9800000, v131
	v_mov_b32_e32 v204, v199
	v_mov_b32_e32 v205, v209
	v_mov_b32_e32 v199, v208
	v_pk_mul_f32 v[218:219], v[204:205], v[204:205]
	v_pk_mul_f32 v[208:209], v[198:199], v[198:199]
	v_fmac_f32_e32 v214, 0xb9800000, v131
	v_pk_mov_b32 v[220:221], v[208:209], v[218:219] op_sel:[1,0]
	v_mov_b32_e32 v209, v219
	v_pk_add_f32 v[208:209], v[220:221], v[208:209]
	v_fmac_f32_e32 v215, 0xb9800000, v131
	v_fmac_f32_e32 v201, 0xb9800000, v131
	v_pk_add_f32 v[218:219], v[208:209], v[208:209] op_sel_hi:[0,1]
	v_fmac_f32_e32 v200, 0xb9800000, v131
	v_mov_b32_e32 v208, v201
	v_mov_b32_e32 v209, v215
	v_mov_b32_e32 v201, v214
	v_pk_mul_f32 v[220:221], v[208:209], v[208:209]
	v_pk_mul_f32 v[214:215], v[200:201], v[200:201]
	v_fmac_f32_e32 v188, 0xb9800000, v131
	v_pk_mov_b32 v[228:229], v[214:215], v[220:221] op_sel:[1,0]
	v_mov_b32_e32 v215, v221
	v_pk_add_f32 v[214:215], v[228:229], v[214:215]
	v_fmac_f32_e32 v189, 0xb9800000, v131
	v_pk_add_f32 v[214:215], v[214:215], v[214:215] op_sel_hi:[0,1]
	v_fmac_f32_e32 v190, 0xb9800000, v131
	v_mul_f32_e32 v214, v188, v188
	v_fmac_f32_e32 v191, 0xb9800000, v131
	v_pk_fma_f32 v[220:221], v[188:189], v[188:189], v[214:215] op_sel_hi:[1,1,0]
	v_mul_f32_e32 v214, v190, v190
	v_pk_fma_f32 v[228:229], v[190:191], v[190:191], v[214:215] op_sel_hi:[1,1,0]
	v_fmac_f32_e32 v184, 0xb9800000, v131
	v_fmac_f32_e32 v180, 0xb9800000, v131
	v_fmac_f32_e32 v186, 0xb9800000, v131
	v_fmac_f32_e32 v182, 0xb9800000, v131
	v_mul_f32_e32 v220, v182, v182
	v_mul_f32_e32 v228, v186, v186
	v_mul_f32_e32 v218, v180, v180
	v_mul_f32_e32 v214, v184, v184
	v_pk_add_f32 v[220:221], v[220:221], v[228:229]
	v_pk_add_f32 v[214:215], v[218:219], v[214:215]
	v_fmac_f32_e32 v210, 0xb9800000, v131
	v_pk_add_f32 v[214:215], v[220:221], v[214:215]
	v_fmac_f32_e32 v211, 0xb9800000, v131
	v_fmac_f32_e32 v195, 0xb9800000, v131
	v_pk_add_f32 v[218:219], v[214:215], v[214:215] op_sel_hi:[0,1]
	v_fmac_f32_e32 v194, 0xb9800000, v131
	v_mov_b32_e32 v214, v195
	v_mov_b32_e32 v215, v211
	v_mov_b32_e32 v195, v210
	v_pk_mul_f32 v[220:221], v[214:215], v[214:215]
	v_pk_mul_f32 v[210:211], v[194:195], v[194:195]
	v_fmac_f32_e32 v164, 0xb9800000, v131
	v_pk_mov_b32 v[228:229], v[210:211], v[220:221] op_sel:[1,0]
	v_mov_b32_e32 v211, v221
	v_pk_add_f32 v[210:211], v[228:229], v[210:211]
	v_fmac_f32_e32 v165, 0xb9800000, v131
	v_pk_add_f32 v[210:211], v[210:211], v[210:211] op_sel_hi:[0,1]
	v_fmac_f32_e32 v166, 0xb9800000, v131
	v_mul_f32_e32 v210, v164, v164
	v_fmac_f32_e32 v167, 0xb9800000, v131
	v_pk_fma_f32 v[220:221], v[164:165], v[164:165], v[210:211] op_sel_hi:[1,1,0]
	v_mul_f32_e32 v210, v166, v166
	v_pk_fma_f32 v[228:229], v[166:167], v[166:167], v[210:211] op_sel_hi:[1,1,0]
	v_fmac_f32_e32 v154, 0xb9800000, v131
	v_fmac_f32_e32 v150, 0xb9800000, v131
	v_fmac_f32_e32 v156, 0xb9800000, v131
	v_fmac_f32_e32 v152, 0xb9800000, v131
	v_mul_f32_e32 v220, v152, v152
	v_mul_f32_e32 v228, v156, v156
	v_mul_f32_e32 v210, v150, v150
	v_mul_f32_e32 v218, v154, v154
	v_pk_add_f32 v[220:221], v[220:221], v[228:229]
	v_pk_add_f32 v[210:211], v[210:211], v[218:219]
	v_fmac_f32_e32 v216, 0xb9800000, v131
	v_fmac_f32_e32 v217, 0xb9800000, v131
	v_fmac_f32_e32 v193, 0xb9800000, v131
	v_pk_add_f32 v[210:211], v[220:221], v[210:211]
	v_fmac_f32_e32 v192, 0xb9800000, v131
	v_mov_b32_e32 v218, v193
	v_mov_b32_e32 v219, v217
	v_mov_b32_e32 v193, v216
	v_pk_add_f32 v[210:211], v[210:211], v[210:211] op_sel_hi:[0,1]
	v_pk_mul_f32 v[220:221], v[218:219], v[218:219]
	v_pk_mul_f32 v[216:217], v[192:193], v[192:193]
	v_fmac_f32_e32 v176, 0xb9800000, v131
	v_pk_mov_b32 v[228:229], v[216:217], v[220:221] op_sel:[1,0]
	v_mov_b32_e32 v217, v221
	v_fmac_f32_e32 v177, 0xb9800000, v131
	v_fmac_f32_e32 v178, 0xb9800000, v131
	v_mul_f32_e32 v210, v176, v176
	v_pk_add_f32 v[216:217], v[228:229], v[216:217]
	v_fmac_f32_e32 v179, 0xb9800000, v131
	v_pk_fma_f32 v[220:221], v[176:177], v[176:177], v[210:211] op_sel_hi:[1,1,0]
	v_mul_f32_e32 v210, v178, v178
	v_pk_add_f32 v[216:217], v[216:217], v[216:217] op_sel_hi:[0,1]
	v_pk_fma_f32 v[228:229], v[178:179], v[178:179], v[210:211] op_sel_hi:[1,1,0]
	v_fmac_f32_e32 v172, 0xb9800000, v131
	v_fmac_f32_e32 v168, 0xb9800000, v131
	v_fmac_f32_e32 v174, 0xb9800000, v131
	v_fmac_f32_e32 v170, 0xb9800000, v131
	v_mul_f32_e32 v220, v170, v170
	v_mul_f32_e32 v228, v174, v174
	v_mul_f32_e32 v216, v168, v168
	v_mul_f32_e32 v210, v172, v172
	v_pk_add_f32 v[220:221], v[220:221], v[228:229]
	v_pk_add_f32 v[210:211], v[216:217], v[210:211]
	v_fmac_f32_e32 v212, 0xb9800000, v131
	v_fmac_f32_e32 v213, 0xb9800000, v131
	v_fmac_f32_e32 v203, 0xb9800000, v131
	v_pk_add_f32 v[210:211], v[220:221], v[210:211]
	v_fmac_f32_e32 v202, 0xb9800000, v131
	v_mov_b32_e32 v216, v203
	v_mov_b32_e32 v217, v213
	v_mov_b32_e32 v203, v212
	v_pk_add_f32 v[210:211], v[210:211], v[210:211] op_sel_hi:[0,1]
	v_pk_mul_f32 v[220:221], v[216:217], v[216:217]
	v_pk_mul_f32 v[212:213], v[202:203], v[202:203]
	v_fmac_f32_e32 v158, 0xb9800000, v131
	v_pk_mov_b32 v[228:229], v[212:213], v[220:221] op_sel:[1,0]
	v_mov_b32_e32 v213, v221
	v_fmac_f32_e32 v159, 0xb9800000, v131
	v_fmac_f32_e32 v160, 0xb9800000, v131
	v_mul_f32_e32 v210, v158, v158
	v_pk_add_f32 v[212:213], v[228:229], v[212:213]
	v_fmac_f32_e32 v161, 0xb9800000, v131
	v_pk_fma_f32 v[220:221], v[158:159], v[158:159], v[210:211] op_sel_hi:[1,1,0]
	v_mul_f32_e32 v210, v160, v160
	v_pk_add_f32 v[212:213], v[212:213], v[212:213] op_sel_hi:[0,1]
	v_pk_fma_f32 v[228:229], v[160:161], v[160:161], v[210:211] op_sel_hi:[1,1,0]
	v_fmac_f32_e32 v146, 0xb9800000, v131
	v_fmac_f32_e32 v142, 0xb9800000, v131
	v_fmac_f32_e32 v148, 0xb9800000, v131
	v_fmac_f32_e32 v144, 0xb9800000, v131
	v_mul_f32_e32 v220, v144, v144
	v_mul_f32_e32 v228, v148, v148
	v_mul_f32_e32 v212, v142, v142
	v_mul_f32_e32 v210, v146, v146
	v_pk_add_f32 v[220:221], v[220:221], v[228:229]
	v_pk_add_f32 v[210:211], v[212:213], v[210:211]
	v_fmac_f32_e32 v206, 0xb9800000, v131
	v_fmac_f32_e32 v207, 0xb9800000, v131
	v_fmac_f32_e32 v197, 0xb9800000, v131
	v_pk_add_f32 v[210:211], v[220:221], v[210:211]
	v_fmac_f32_e32 v196, 0xb9800000, v131
	v_mov_b32_e32 v220, v197
	v_mov_b32_e32 v221, v207
	v_mov_b32_e32 v197, v206
	v_pk_mul_f32 v[212:213], v[220:221], v[220:221]
	v_pk_mul_f32 v[206:207], v[196:197], v[196:197]
	v_fmac_f32_e32 v138, 0xb9800000, v131
	v_pk_mov_b32 v[228:229], v[206:207], v[212:213] op_sel:[1,0]
	v_mov_b32_e32 v207, v213
	v_pk_add_f32 v[206:207], v[228:229], v[206:207]
	v_fmac_f32_e32 v139, 0xb9800000, v131
	v_pk_add_f32 v[206:207], v[206:207], v[206:207] op_sel_hi:[0,1]
	v_fmac_f32_e32 v140, 0xb9800000, v131
	v_mul_f32_e32 v206, v138, v138
	v_fmac_f32_e32 v141, 0xb9800000, v131
	v_pk_fma_f32 v[212:213], v[138:139], v[138:139], v[206:207] op_sel_hi:[1,1,0]
	v_mul_f32_e32 v206, v140, v140
	v_pk_add_f32 v[210:211], v[210:211], v[210:211] op_sel_hi:[0,1]
	v_pk_fma_f32 v[228:229], v[140:141], v[140:141], v[206:207] op_sel_hi:[1,1,0]
	v_fmac_f32_e32 v134, 0xb9800000, v131
	v_fmac_f32_e32 v130, 0xb9800000, v131
	v_fmac_f32_e32 v136, 0xb9800000, v131
	v_fmac_f32_e32 v132, 0xb9800000, v131
	v_mul_f32_e32 v212, v132, v132
	v_mul_f32_e32 v228, v136, v136
	v_mul_f32_e32 v206, v130, v130
	v_mul_f32_e32 v210, v134, v134
	v_pk_add_f32 v[212:213], v[212:213], v[228:229]
	v_pk_add_f32 v[206:207], v[206:207], v[210:211]
	v_mov_b32_e32 v183, v186
	v_pk_add_f32 v[206:207], v[212:213], v[206:207]
	v_mov_b32_e32 v181, v184
	v_add_f32_e32 v131, v206, v207
	v_mov_b32_e32 v153, v156
	v_mov_b32_e32 v151, v154
	v_add_f32_dpp v131, v131, v131 quad_perm:[1,0,3,2] row_mask:0xf bank_mask:0xf bound_ctrl:1
	v_mov_b32_e32 v171, v174
	v_mov_b32_e32 v169, v172
	v_add_f32_dpp v131, v131, v131 quad_perm:[2,3,0,1] row_mask:0xf bank_mask:0xf bound_ctrl:1
	s_nop 1
	v_add_f32_dpp v131, v131, v131 row_half_mirror row_mask:0xf bank_mask:0xf bound_ctrl:1
	s_nop 1
	v_add_f32_dpp v131, v131, v131 row_mirror row_mask:0xf bank_mask:0xf bound_ctrl:1
	ds_bpermute_b32 v133, v137, v131
	s_waitcnt lgkmcnt(0)
	v_add_f32_e32 v131, v131, v133
	ds_bpermute_b32 v133, v135, v131
	s_waitcnt lgkmcnt(0)
	v_add_f32_e32 v131, v131, v133
	v_fmamk_f32 v131, v131, 0x39800000, v225
	v_mul_f32_e32 v133, 0x4f800000, v131
	v_cmp_gt_f32_e32 vcc, s0, v131
	s_nop 1
	v_cndmask_b32_e32 v131, v131, v133, vcc
	v_sqrt_f32_e32 v133, v131
	s_nop 0
	v_add_u32_e32 v143, -1, v133
	v_fma_f32 v145, -v143, v133, v131
	v_cmp_ge_f32_e64 s[0:1], 0, v145
	v_add_u32_e32 v145, 1, v133
	s_nop 0
	v_cndmask_b32_e64 v143, v133, v143, s[0:1]
	v_fma_f32 v133, -v145, v133, v131
	v_cmp_lt_f32_e64 s[0:1], 0, v133
	s_nop 1
	v_cndmask_b32_e64 v133, v143, v145, s[0:1]
	v_mul_f32_e32 v143, 0x37800000, v133
	v_cndmask_b32_e32 v133, v133, v143, vcc
	v_cmp_class_f32_e32 vcc, v131, v226
	s_nop 1
	v_cndmask_b32_e32 v131, v133, v131, vcc
	v_div_scale_f32 v133, s[0:1], v131, v131, 1.0
	v_rcp_f32_e32 v143, v133
	s_add_u32 s0, s16, s12
	s_addc_u32 s1, s37, s13
	v_lshl_add_u64 v[230:231], s[0:1], 0, v[162:163]
	v_fma_f32 v145, -v133, v143, 1.0
	v_fmac_f32_e32 v143, v145, v143
	v_div_scale_f32 v145, vcc, 1.0, v131, 1.0
	v_mul_f32_e32 v147, v145, v143
	v_fma_f32 v149, -v133, v147, v145
	v_fmac_f32_e32 v147, v149, v143
	v_fma_f32 v133, -v133, v147, v145
	v_div_fmas_f32 v133, v133, v143, v147
	v_div_fixup_f32 v228, v133, v131, 1.0
	v_pk_mul_f32 v[198:199], v[198:199], v[228:229] op_sel_hi:[1,0]
	v_pk_mul_f32 v[204:205], v[204:205], v[228:229] op_sel_hi:[1,0]
	v_pk_fma_f32 v[206:207], v[4:5], v[198:199], v[12:13]
	v_pk_mul_f32 v[198:199], v[200:201], v[228:229] op_sel_hi:[1,0]
	v_pk_mul_f32 v[200:201], v[208:209], v[228:229] op_sel_hi:[1,0]
	v_pk_fma_f32 v[204:205], v[6:7], v[204:205], v[14:15]
	v_pk_fma_f32 v[210:211], v[2:3], v[200:201], v[10:11]
	v_pk_fma_f32 v[212:213], v[0:1], v[198:199], v[8:9]
	v_pk_mul_f32 v[162:163], v[188:189], v[228:229] op_sel_hi:[1,0]
	v_cvt_pk_bf16_f32 v198, v206, v207
	v_cvt_pk_bf16_f32 v199, v204, v205
	v_cvt_pk_bf16_f32 v200, v212, v213
	v_cvt_pk_bf16_f32 v201, v210, v211
	v_pk_mul_f32 v[188:189], v[190:191], v[228:229] op_sel_hi:[1,0]
	v_pk_fma_f32 v[190:191], v[20:21], v[162:163], v[28:29]
	v_pk_mul_f32 v[162:163], v[182:183], v[228:229] op_sel_hi:[1,0]
	v_pk_mul_f32 v[180:181], v[180:181], v[228:229] op_sel_hi:[1,0]
	global_store_dwordx4 v[230:231], v[198:201], off
	v_pk_fma_f32 v[188:189], v[22:23], v[188:189], v[30:31]
	v_pk_fma_f32 v[208:209], v[16:17], v[162:163], v[24:25]
	v_pk_fma_f32 v[200:201], v[18:19], v[180:181], v[26:27]
	v_cvt_pk_bf16_f32 v180, v190, v191
	v_cvt_pk_bf16_f32 v181, v188, v189
	v_cvt_pk_bf16_f32 v182, v208, v209
	v_cvt_pk_bf16_f32 v183, v200, v201
	v_pk_mul_f32 v[162:163], v[194:195], v[228:229] op_sel_hi:[1,0]
	global_store_dwordx4 v[230:231], v[180:183], off offset:1024
	v_pk_mul_f32 v[152:153], v[152:153], v[228:229] op_sel_hi:[1,0]
	v_pk_mul_f32 v[150:151], v[150:151], v[228:229] op_sel_hi:[1,0]
	v_pk_mul_f32 v[180:181], v[214:215], v[228:229] op_sel_hi:[1,0]
	v_pk_fma_f32 v[182:183], v[56:57], v[162:163], v[68:69]
	v_pk_mul_f32 v[162:163], v[164:165], v[228:229] op_sel_hi:[1,0]
	v_pk_mul_f32 v[164:165], v[166:167], v[228:229] op_sel_hi:[1,0]
	v_pk_fma_f32 v[180:181], v[58:59], v[180:181], v[70:71]
	v_pk_fma_f32 v[194:195], v[34:35], v[164:165], v[46:47]
	v_pk_fma_f32 v[198:199], v[32:33], v[162:163], v[44:45]
	v_cvt_pk_bf16_f32 v162, v182, v183
	v_cvt_pk_bf16_f32 v163, v180, v181
	v_cvt_pk_bf16_f32 v164, v198, v199
	v_cvt_pk_bf16_f32 v165, v194, v195
	v_max_f32_e64 v143, |v210|, |v211|
	global_store_dwordx4 v[230:231], v[162:165], off offset:2048
	v_max_f32_e64 v131, |v206|, |v207|
	v_max_f32_e64 v133, |v204|, |v205|
	v_pk_fma_f32 v[162:163], v[38:39], v[150:151], v[50:51]
	v_pk_fma_f32 v[164:165], v[36:37], v[152:153], v[48:49]
	v_pk_mul_f32 v[150:151], v[192:193], v[228:229] op_sel_hi:[1,0]
	v_pk_mul_f32 v[152:153], v[218:219], v[228:229] op_sel_hi:[1,0]
	v_max3_f32 v143, |v212|, |v213|, v143
	v_max_f32_e64 v145, |v200|, |v201|
	v_pk_fma_f32 v[184:185], v[42:43], v[152:153], v[54:55]
	v_pk_fma_f32 v[186:187], v[40:41], v[150:151], v[52:53]
	v_max3_f32 v131, v131, v133, v143
	v_max_f32_e64 v133, |v190|, |v191|
	v_max_f32_e64 v143, |v188|, |v189|
	v_max3_f32 v145, |v208|, |v209|, v145
	v_cvt_pk_bf16_f32 v150, v164, v165
	v_cvt_pk_bf16_f32 v151, v162, v163
	v_cvt_pk_bf16_f32 v152, v186, v187
	v_cvt_pk_bf16_f32 v153, v184, v185
	v_max3_f32 v133, v133, v143, v145
	v_max_f32_e64 v145, |v194|, |v195|
	global_store_dwordx4 v[230:231], v[150:153], off offset:3072
	v_pk_mul_f32 v[154:155], v[170:171], v[228:229] op_sel_hi:[1,0]
	v_pk_mul_f32 v[156:157], v[168:169], v[228:229] op_sel_hi:[1,0]
	v_pk_mul_f32 v[152:153], v[176:177], v[228:229] op_sel_hi:[1,0]
	v_pk_mul_f32 v[150:151], v[178:179], v[228:229] op_sel_hi:[1,0]
	v_max3_f32 v131, v131, 0, v133
	v_max_f32_e64 v133, |v182|, |v183|
	v_max_f32_e64 v143, |v180|, |v181|
	v_max3_f32 v145, |v198|, |v199|, v145
	v_max_f32_e64 v147, |v184|, |v185|
	v_pk_fma_f32 v[150:151], v[62:63], v[150:151], v[74:75]
	v_pk_fma_f32 v[152:153], v[60:61], v[152:153], v[72:73]
	v_pk_fma_f32 v[166:167], v[66:67], v[156:157], v[78:79]
	v_pk_fma_f32 v[168:169], v[64:65], v[154:155], v[76:77]
	v_add_co_u32_e32 v174, vcc, s14, v230
	v_max3_f32 v133, v133, v143, v145
	v_max_f32_e64 v143, |v164|, |v165|
	v_max_f32_e64 v145, |v162|, |v163|
	v_max3_f32 v147, |v186|, |v187|, v147
	v_cvt_pk_bf16_f32 v154, v152, v153
	v_cvt_pk_bf16_f32 v155, v150, v151
	v_cvt_pk_bf16_f32 v156, v168, v169
	v_cvt_pk_bf16_f32 v157, v166, v167
	v_addc_co_u32_e32 v175, vcc, 0, v231, vcc
	v_pk_mul_f32 v[170:171], v[158:159], v[228:229] op_sel_hi:[1,0]
	v_pk_mul_f32 v[158:159], v[160:161], v[228:229] op_sel_hi:[1,0]
	v_max3_f32 v143, v143, v145, v147
	global_store_dwordx4 v[174:175], v[154:157], off
	v_max_f32_e64 v145, |v166|, |v167|
	v_pk_fma_f32 v[158:159], v[86:87], v[158:159], v[94:95]
	v_pk_mul_f32 v[156:157], v[202:203], v[228:229] op_sel_hi:[1,0]
	v_pk_mul_f32 v[154:155], v[216:217], v[228:229] op_sel_hi:[1,0]
	v_max3_f32 v131, v131, v133, v143
	v_max_f32_e64 v133, |v152|, |v153|
	v_max_f32_e64 v143, |v150|, |v151|
	v_max3_f32 v145, |v168|, |v169|, v145
	v_pk_fma_f32 v[154:155], v[82:83], v[154:155], v[90:91]
	v_pk_fma_f32 v[156:157], v[80:81], v[156:157], v[88:89]
	v_pk_fma_f32 v[160:161], v[84:85], v[170:171], v[92:93]
	v_max_f32_e64 v147, |v158|, |v159|
	v_max3_f32 v133, v133, v143, v145
	v_max_f32_e64 v143, |v156|, |v157|
	v_max_f32_e64 v145, |v154|, |v155|
	v_max3_f32 v147, |v160|, |v161|, v147
	v_max3_f32 v143, v143, v145, v147
	v_max3_f32 v176, v131, v133, v143
	v_mov_b32_e32 v145, v148
	v_mov_b32_e32 v143, v146
	v_pk_mul_f32 v[146:147], v[220:221], v[228:229] op_sel_hi:[1,0]
	v_cvt_pk_bf16_f32 v170, v156, v157
	v_cvt_pk_bf16_f32 v171, v154, v155
	v_cvt_pk_bf16_f32 v172, v160, v161
	v_cvt_pk_bf16_f32 v173, v158, v159
	v_pk_mul_f32 v[144:145], v[144:145], v[228:229] op_sel_hi:[1,0]
	v_pk_mul_f32 v[142:143], v[142:143], v[228:229] op_sel_hi:[1,0]
	v_pk_mul_f32 v[148:149], v[196:197], v[228:229] op_sel_hi:[1,0]
	v_pk_fma_f32 v[146:147], v[102:103], v[146:147], v[110:111]
	global_store_dwordx4 v[174:175], v[170:173], off offset:1024
	v_pk_fma_f32 v[142:143], v[98:99], v[142:143], v[106:107]
	v_pk_fma_f32 v[144:145], v[96:97], v[144:145], v[104:105]
	v_pk_fma_f32 v[148:149], v[100:101], v[148:149], v[108:109]
	v_max_f32_e64 v172, |v146|, |v147|
	v_max_f32_e64 v131, |v144|, |v145|
	v_max_f32_e64 v133, |v142|, |v143|
	v_max3_f32 v172, |v148|, |v149|, v172
	v_max3_f32 v177, v131, v133, v172
	v_mov_b32_e32 v131, v134
	v_mov_b32_e32 v133, v136
	v_pk_mul_f32 v[130:131], v[130:131], v[228:229] op_sel_hi:[1,0]
	v_pk_mul_f32 v[172:173], v[138:139], v[228:229] op_sel_hi:[1,0]
	v_pk_mul_f32 v[138:139], v[140:141], v[228:229] op_sel_hi:[1,0]
	v_pk_mul_f32 v[132:133], v[132:133], v[228:229] op_sel_hi:[1,0]
	v_pk_fma_f32 v[130:131], v[118:119], v[130:131], v[126:127]
	v_pk_fma_f32 v[138:139], v[114:115], v[138:139], v[122:123]
	v_pk_fma_f32 v[140:141], v[112:113], v[172:173], v[120:121]
	v_pk_fma_f32 v[132:133], v[116:117], v[132:133], v[124:125]
	v_max_f32_e64 v172, |v130|, |v131|
	v_max_f32_e64 v134, |v140|, |v141|
	v_max_f32_e64 v136, |v138|, |v139|
	v_max3_f32 v172, |v132|, |v133|, v172
	v_max3_f32 v134, v134, v136, v172
	v_max3_f32 v134, v176, v177, v134
	v_mov_b32_e32 v136, 0
	v_cvt_pk_bf16_f32 v170, v144, v145
	v_cvt_pk_bf16_f32 v171, v142, v143
	v_mov_b32_dpp v136, v134 quad_perm:[1,0,3,2] row_mask:0xf bank_mask:0xf
	v_max_f32_e32 v136, v136, v136
	v_max_f32_e32 v134, v134, v136
	v_mov_b32_e32 v136, 0
	v_cvt_pk_bf16_f32 v172, v148, v149
	v_cvt_pk_bf16_f32 v173, v146, v147
	v_mov_b32_dpp v136, v134 quad_perm:[2,3,0,1] row_mask:0xf bank_mask:0xf
	v_max_f32_e32 v136, v136, v136
	v_max_f32_e32 v134, v134, v136
	v_mov_b32_e32 v136, 0
	global_store_dwordx4 v[174:175], v[170:173], off offset:2048
	v_cmp_eq_u32_e32 vcc, 0, v223
	v_mov_b32_dpp v136, v134 row_half_mirror row_mask:0xf bank_mask:0xf
	v_max_f32_e32 v136, v136, v136
	v_max_f32_e32 v134, v134, v136
	v_mov_b32_e32 v136, 0
	s_nop 1
	v_mov_b32_dpp v136, v134 row_mirror row_mask:0xf bank_mask:0xf
	v_max_f32_e32 v136, v136, v136
	v_max_f32_e32 v136, v134, v136
	ds_bpermute_b32 v137, v137, v136
	v_cvt_pk_bf16_f32 v134, v140, v141
	s_waitcnt lgkmcnt(0)
	v_max_f32_e32 v137, v137, v137
	v_max_f32_e32 v170, v136, v137
	ds_bpermute_b32 v171, v135, v170
	v_cvt_pk_bf16_f32 v135, v138, v139
	v_cvt_pk_bf16_f32 v136, v132, v133
	v_cvt_pk_bf16_f32 v137, v130, v131
	global_store_dwordx4 v[174:175], v[134:137], off offset:3072
	s_waitcnt lgkmcnt(0)
	s_nop 0
	v_max_f32_e32 v134, v171, v171
	v_max_f32_e32 v134, v170, v134
	s_and_saveexec_b64 s[0:1], vcc
	s_cbranch_execz .LBB0_479
	s_lshl_b64 s[12:13], s[10:11], 2
	v_readlane_b32 s18, v254, 45
	v_readlane_b32 s19, v254, 46
	s_add_u32 s12, s18, s12
	s_addc_u32 s13, s19, s13
	v_mul_f32_e32 v135, 0x3c010204, v134
	global_store_dword v224, v135, s[12:13]
